# op
# baseline (speedup 1.0000x reference)
; DEVI void ph_outproj(const Params& p, int layer, char* shm) {
;     ...
;     auto ep = [&](Acc256& acc) {
;         EPI_IDX;
;       constexpr float osc = 1.0f;
; #pragma unroll
;       for (int ai = 0; ai < 2; ++ai)
; #pragma unroll
;         for (int bj = 0; bj < 2; ++bj)
; #pragma unroll
;           for (int m = 0; m < 4; ++m)
; #pragma unroll
;             for (int n = 0; n < 2; ++n) {
;               size_t off = (size_t)(brow + ai * 128 + wr * 64 + m * 16 + fr) * 1024 + bcol + bj * 128 + wc * 32 + n * 16 + fq * 4;
;               float4 r = *reinterpret_cast<const float4*>(resid + off);
;               float4 o;
;               o.x = DN_ALPHA * r.x + acc[ai][bj][m][n][0] * osc;
;               o.y = DN_ALPHA * r.y + acc[ai][bj][m][n][1] * osc;
;               o.z = DN_ALPHA * r.z + acc[ai][bj][m][n][2] * osc;
;               o.w = DN_ALPHA * r.w + acc[ai][bj][m][n][3] * osc;
;               *reinterpret_cast<float4*>(outp + off) = o;
;             }
;     };
.LBB0_996:
	v_mov_b32_e32 v128, v214
	v_readlane_b32 s8, v242, 42
	v_and_b32_e32 v129, 15, v128
	v_ashrrev_i32_e32 v130, 2, v128
	v_and_or_b32 v129, v130, s45, v129
	v_lshrrev_b32_e32 v130, 1, v128
	v_lshrrev_b32_e32 v128, 2, v128
	v_and_b32_e32 v130, 0x60, v130
	v_and_b32_e32 v131, 12, v128
	v_add_u32_e32 v128, s58, v129
	v_ashrrev_i32_e32 v129, 31, v128
	v_or3_b32 v130, v130, v131, s57
	v_lshlrev_b64 v[134:135], 12, v[128:129]
	v_lshlrev_b32_e32 v129, 2, v130
	v_or_b32_e32 v134, v134, v129
	v_readlane_b32 s9, v242, 43
	v_readlane_b32 s60, v242, 0
	v_readlane_b32 s66, v242, 6
	v_lshl_add_u64 v[136:137], s[8:9], 0, v[134:135]
	v_readlane_b32 s67, v242, 7
	s_andn2_b64 vcc, exec, s[2:3]
	s_mov_b64 s[2:3], 0
	v_readlane_b32 s10, v242, 44
	v_readlane_b32 s11, v242, 45
	v_readlane_b32 s12, v242, 46
	v_readlane_b32 s13, v242, 47
	v_readlane_b32 s14, v242, 48
	v_readlane_b32 s15, v242, 49
	v_readlane_b32 s16, v242, 50
	v_readlane_b32 s17, v242, 51
	v_readlane_b32 s18, v242, 52
	v_readlane_b32 s19, v242, 53
	v_readlane_b32 s20, v242, 54
	v_readlane_b32 s21, v242, 55
	v_readlane_b32 s22, v242, 56
	v_readlane_b32 s23, v242, 57
	v_readlane_b32 s61, v242, 1
	v_readlane_b32 s62, v242, 2
	v_readlane_b32 s63, v242, 3
	v_readlane_b32 s64, v242, 4
	v_readlane_b32 s65, v242, 5
	v_lshl_or_b32 v243, v128, 12, v129
	v_add_u32_e32 v244, 16, v128
	v_lshl_or_b32 v244, v244, 12, v129
	v_add_u32_e32 v245, 32, v128
	v_lshl_or_b32 v245, v245, 12, v129
	v_add_u32_e32 v246, 48, v128
	v_lshl_or_b32 v246, v246, 12, v129
	v_add_u32_e32 v247, 128, v128
	v_lshl_or_b32 v247, v247, 12, v129
	v_add_u32_e32 v248, 144, v128
	v_lshl_or_b32 v248, v248, 12, v129
	v_add_u32_e32 v249, 160, v128
	v_lshl_or_b32 v249, v249, 12, v129
	v_add_u32_e32 v250, 176, v128
	v_lshl_or_b32 v250, v250, 12, v129
	global_load_dwordx4 v[130:133], v243, s[8:9]
	global_load_dwordx4 v[134:137], v243, s[8:9] offset:64
	global_load_dwordx4 v[252:255], v244, s[8:9]
	s_waitcnt vmcnt(2)
	v_pk_fma_f32 v[124:125], v[130:131], s[28:29], v[124:125] op_sel_hi:[1,0,1]
	v_pk_fma_f32 v[126:127], v[132:133], s[28:29], v[126:127] op_sel_hi:[1,0,1]
	global_store_dwordx4 v243, v[124:127], s[66:67]
	global_load_dwordx4 v[124:127], v244, s[8:9] offset:64
	s_waitcnt vmcnt(3)
	v_pk_fma_f32 v[120:121], v[134:135], s[28:29], v[120:121] op_sel_hi:[1,0,1]
	v_pk_fma_f32 v[122:123], v[136:137], s[28:29], v[122:123] op_sel_hi:[1,0,1]
	global_store_dwordx4 v243, v[120:123], s[66:67] offset:64
	global_load_dwordx4 v[120:123], v245, s[8:9]
	s_waitcnt vmcnt(4)
	v_pk_fma_f32 v[116:117], v[252:253], s[28:29], v[116:117] op_sel_hi:[1,0,1]
	v_pk_fma_f32 v[118:119], v[254:255], s[28:29], v[118:119] op_sel_hi:[1,0,1]
	global_store_dwordx4 v244, v[116:119], s[66:67]
	global_load_dwordx4 v[116:119], v245, s[8:9] offset:64
	s_waitcnt vmcnt(4)
	v_pk_fma_f32 v[112:113], v[124:125], s[28:29], v[112:113] op_sel_hi:[1,0,1]
	v_pk_fma_f32 v[114:115], v[126:127], s[28:29], v[114:115] op_sel_hi:[1,0,1]
	global_store_dwordx4 v244, v[112:115], s[66:67] offset:64
	global_load_dwordx4 v[112:115], v246, s[8:9]
	s_waitcnt vmcnt(4)
	v_pk_fma_f32 v[108:109], v[120:121], s[28:29], v[108:109] op_sel_hi:[1,0,1]
	v_pk_fma_f32 v[110:111], v[122:123], s[28:29], v[110:111] op_sel_hi:[1,0,1]
	global_store_dwordx4 v245, v[108:111], s[66:67]
	global_load_dwordx4 v[108:111], v246, s[8:9] offset:64
	s_waitcnt vmcnt(4)
	v_pk_fma_f32 v[104:105], v[116:117], s[28:29], v[104:105] op_sel_hi:[1,0,1]
	v_pk_fma_f32 v[106:107], v[118:119], s[28:29], v[106:107] op_sel_hi:[1,0,1]
	global_store_dwordx4 v245, v[104:107], s[66:67] offset:64
	global_load_dwordx4 v[104:107], v243, s[8:9] offset:512
	s_waitcnt vmcnt(4)
	v_pk_fma_f32 v[100:101], v[112:113], s[28:29], v[100:101] op_sel_hi:[1,0,1]
	v_pk_fma_f32 v[102:103], v[114:115], s[28:29], v[102:103] op_sel_hi:[1,0,1]
	global_store_dwordx4 v246, v[100:103], s[66:67]
	global_load_dwordx4 v[100:103], v243, s[8:9] offset:576
	s_waitcnt vmcnt(4)
	v_pk_fma_f32 v[96:97], v[108:109], s[28:29], v[96:97] op_sel_hi:[1,0,1]
	v_pk_fma_f32 v[98:99], v[110:111], s[28:29], v[98:99] op_sel_hi:[1,0,1]
	global_store_dwordx4 v246, v[96:99], s[66:67] offset:64
	global_load_dwordx4 v[96:99], v244, s[8:9] offset:512
	s_waitcnt vmcnt(4)
	v_pk_fma_f32 v[92:93], v[104:105], s[28:29], v[92:93] op_sel_hi:[1,0,1]
	v_pk_fma_f32 v[94:95], v[106:107], s[28:29], v[94:95] op_sel_hi:[1,0,1]
	global_store_dwordx4 v243, v[92:95], s[66:67] offset:512
	global_load_dwordx4 v[92:95], v244, s[8:9] offset:576
	s_waitcnt vmcnt(4)
	v_pk_fma_f32 v[88:89], v[100:101], s[28:29], v[88:89] op_sel_hi:[1,0,1]
	v_pk_fma_f32 v[90:91], v[102:103], s[28:29], v[90:91] op_sel_hi:[1,0,1]
	global_store_dwordx4 v243, v[88:91], s[66:67] offset:576
	global_load_dwordx4 v[88:91], v245, s[8:9] offset:512
	s_waitcnt vmcnt(4)
	v_pk_fma_f32 v[84:85], v[96:97], s[28:29], v[84:85] op_sel_hi:[1,0,1]
	v_pk_fma_f32 v[86:87], v[98:99], s[28:29], v[86:87] op_sel_hi:[1,0,1]
	global_store_dwordx4 v244, v[84:87], s[66:67] offset:512
	global_load_dwordx4 v[84:87], v245, s[8:9] offset:576
	s_waitcnt vmcnt(4)
	v_pk_fma_f32 v[80:81], v[92:93], s[28:29], v[80:81] op_sel_hi:[1,0,1]
	v_pk_fma_f32 v[82:83], v[94:95], s[28:29], v[82:83] op_sel_hi:[1,0,1]
	global_store_dwordx4 v244, v[80:83], s[66:67] offset:576
	global_load_dwordx4 v[80:83], v246, s[8:9] offset:512
	s_waitcnt vmcnt(4)
; DEVI void ph_outproj(const Params& p, int layer, char* shm) {
;     ...
;     auto ep = [&](Acc256& acc) {
;         EPI_IDX;
;       constexpr float osc = 1.0f;
; #pragma unroll
;       for (int ai = 0; ai < 2; ++ai)
; #pragma unroll
;         for (int bj = 0; bj < 2; ++bj)
; #pragma unroll
;           for (int m = 0; m < 4; ++m)
; #pragma unroll
;             for (int n = 0; n < 2; ++n) {
;               size_t off = (size_t)(brow + ai * 128 + wr * 64 + m * 16 + fr) * 1024 + bcol + bj * 128 + wc * 32 + n * 16 + fq * 4;
;               float4 r = *reinterpret_cast<const float4*>(resid + off);
;               float4 o;
;               o.x = DN_ALPHA * r.x + acc[ai][bj][m][n][0] * osc;
;               o.y = DN_ALPHA * r.y + acc[ai][bj][m][n][1] * osc;
;               o.z = DN_ALPHA * r.z + acc[ai][bj][m][n][2] * osc;
;               o.w = DN_ALPHA * r.w + acc[ai][bj][m][n][3] * osc;
;               *reinterpret_cast<float4*>(outp + off) = o;
;             }
;     };
	v_pk_fma_f32 v[76:77], v[88:89], s[28:29], v[76:77] op_sel_hi:[1,0,1]
	v_pk_fma_f32 v[78:79], v[90:91], s[28:29], v[78:79] op_sel_hi:[1,0,1]
	global_store_dwordx4 v245, v[76:79], s[66:67] offset:512
	global_load_dwordx4 v[76:79], v246, s[8:9] offset:576
	s_waitcnt vmcnt(4)
	v_pk_fma_f32 v[72:73], v[84:85], s[28:29], v[72:73] op_sel_hi:[1,0,1]
	v_pk_fma_f32 v[74:75], v[86:87], s[28:29], v[74:75] op_sel_hi:[1,0,1]
	global_store_dwordx4 v245, v[72:75], s[66:67] offset:576
	global_load_dwordx4 v[72:75], v247, s[8:9]
	s_waitcnt vmcnt(4)
	v_pk_fma_f32 v[68:69], v[80:81], s[28:29], v[68:69] op_sel_hi:[1,0,1]
	v_pk_fma_f32 v[70:71], v[82:83], s[28:29], v[70:71] op_sel_hi:[1,0,1]
	global_store_dwordx4 v246, v[68:71], s[66:67] offset:512
	global_load_dwordx4 v[68:71], v247, s[8:9] offset:64
	s_waitcnt vmcnt(4)
	v_pk_fma_f32 v[64:65], v[76:77], s[28:29], v[64:65] op_sel_hi:[1,0,1]
	v_pk_fma_f32 v[66:67], v[78:79], s[28:29], v[66:67] op_sel_hi:[1,0,1]
	global_store_dwordx4 v246, v[64:67], s[66:67] offset:576
	global_load_dwordx4 v[64:67], v248, s[8:9]
	s_waitcnt vmcnt(4)
	v_pk_fma_f32 v[60:61], v[72:73], s[28:29], v[60:61] op_sel_hi:[1,0,1]
	v_pk_fma_f32 v[62:63], v[74:75], s[28:29], v[62:63] op_sel_hi:[1,0,1]
	global_store_dwordx4 v247, v[60:63], s[66:67]
	global_load_dwordx4 v[60:63], v248, s[8:9] offset:64
	s_waitcnt vmcnt(4)
	v_pk_fma_f32 v[56:57], v[68:69], s[28:29], v[56:57] op_sel_hi:[1,0,1]
	v_pk_fma_f32 v[58:59], v[70:71], s[28:29], v[58:59] op_sel_hi:[1,0,1]
	global_store_dwordx4 v247, v[56:59], s[66:67] offset:64
	global_load_dwordx4 v[56:59], v249, s[8:9]
	s_waitcnt vmcnt(4)
	v_pk_fma_f32 v[52:53], v[64:65], s[28:29], v[52:53] op_sel_hi:[1,0,1]
	v_pk_fma_f32 v[54:55], v[66:67], s[28:29], v[54:55] op_sel_hi:[1,0,1]
	global_store_dwordx4 v248, v[52:55], s[66:67]
	global_load_dwordx4 v[52:55], v249, s[8:9] offset:64
	s_waitcnt vmcnt(4)
	v_pk_fma_f32 v[48:49], v[60:61], s[28:29], v[48:49] op_sel_hi:[1,0,1]
	v_pk_fma_f32 v[50:51], v[62:63], s[28:29], v[50:51] op_sel_hi:[1,0,1]
	global_store_dwordx4 v248, v[48:51], s[66:67] offset:64
	global_load_dwordx4 v[48:51], v250, s[8:9]
	s_waitcnt vmcnt(4)
	v_pk_fma_f32 v[44:45], v[56:57], s[28:29], v[44:45] op_sel_hi:[1,0,1]
	v_pk_fma_f32 v[46:47], v[58:59], s[28:29], v[46:47] op_sel_hi:[1,0,1]
	global_store_dwordx4 v249, v[44:47], s[66:67]
	global_load_dwordx4 v[44:47], v250, s[8:9] offset:64
	s_waitcnt vmcnt(4)
	v_pk_fma_f32 v[40:41], v[52:53], s[28:29], v[40:41] op_sel_hi:[1,0,1]
	v_pk_fma_f32 v[42:43], v[54:55], s[28:29], v[42:43] op_sel_hi:[1,0,1]
	global_store_dwordx4 v249, v[40:43], s[66:67] offset:64
	global_load_dwordx4 v[40:43], v247, s[8:9] offset:512
	s_waitcnt vmcnt(4)
	v_pk_fma_f32 v[36:37], v[48:49], s[28:29], v[36:37] op_sel_hi:[1,0,1]
	v_pk_fma_f32 v[38:39], v[50:51], s[28:29], v[38:39] op_sel_hi:[1,0,1]
	global_store_dwordx4 v250, v[36:39], s[66:67]
	global_load_dwordx4 v[36:39], v247, s[8:9] offset:576
	s_waitcnt vmcnt(4)
	v_pk_fma_f32 v[32:33], v[44:45], s[28:29], v[32:33] op_sel_hi:[1,0,1]
	v_pk_fma_f32 v[34:35], v[46:47], s[28:29], v[34:35] op_sel_hi:[1,0,1]
	global_store_dwordx4 v250, v[32:35], s[66:67] offset:64
	global_load_dwordx4 v[32:35], v248, s[8:9] offset:512
	s_waitcnt vmcnt(4)
	v_pk_fma_f32 v[28:29], v[40:41], s[28:29], v[28:29] op_sel_hi:[1,0,1]
	v_pk_fma_f32 v[30:31], v[42:43], s[28:29], v[30:31] op_sel_hi:[1,0,1]
	global_store_dwordx4 v247, v[28:31], s[66:67] offset:512
	global_load_dwordx4 v[28:31], v248, s[8:9] offset:576
	s_waitcnt vmcnt(4)
	v_pk_fma_f32 v[24:25], v[36:37], s[28:29], v[24:25] op_sel_hi:[1,0,1]
	v_pk_fma_f32 v[26:27], v[38:39], s[28:29], v[26:27] op_sel_hi:[1,0,1]
	global_store_dwordx4 v247, v[24:27], s[66:67] offset:576
	global_load_dwordx4 v[24:27], v249, s[8:9] offset:512
	s_waitcnt vmcnt(4)
	v_pk_fma_f32 v[20:21], v[32:33], s[28:29], v[20:21] op_sel_hi:[1,0,1]
	v_pk_fma_f32 v[22:23], v[34:35], s[28:29], v[22:23] op_sel_hi:[1,0,1]
	global_store_dwordx4 v248, v[20:23], s[66:67] offset:512
	global_load_dwordx4 v[20:23], v249, s[8:9] offset:576
	s_waitcnt vmcnt(4)
	v_pk_fma_f32 v[16:17], v[28:29], s[28:29], v[16:17] op_sel_hi:[1,0,1]
	v_pk_fma_f32 v[18:19], v[30:31], s[28:29], v[18:19] op_sel_hi:[1,0,1]
	global_store_dwordx4 v248, v[16:19], s[66:67] offset:576
	global_load_dwordx4 v[16:19], v250, s[8:9] offset:512
	s_waitcnt vmcnt(4)
	v_pk_fma_f32 v[12:13], v[24:25], s[28:29], v[12:13] op_sel_hi:[1,0,1]
	v_pk_fma_f32 v[14:15], v[26:27], s[28:29], v[14:15] op_sel_hi:[1,0,1]
	global_store_dwordx4 v249, v[12:15], s[66:67] offset:512
	global_load_dwordx4 v[12:15], v250, s[8:9] offset:576
	s_waitcnt vmcnt(4)
	v_pk_fma_f32 v[8:9], v[20:21], s[28:29], v[8:9] op_sel_hi:[1,0,1]
	v_pk_fma_f32 v[10:11], v[22:23], s[28:29], v[10:11] op_sel_hi:[1,0,1]
	global_store_dwordx4 v249, v[8:11], s[66:67] offset:576
	s_waitcnt vmcnt(3)
	v_pk_fma_f32 v[4:5], v[16:17], s[28:29], v[4:5] op_sel_hi:[1,0,1]
	v_pk_fma_f32 v[6:7], v[18:19], s[28:29], v[6:7] op_sel_hi:[1,0,1]
	global_store_dwordx4 v250, v[4:7], s[66:67] offset:512
	s_waitcnt vmcnt(2)
	v_pk_fma_f32 v[0:1], v[12:13], s[28:29], v[0:1] op_sel_hi:[1,0,1]
	v_pk_fma_f32 v[2:3], v[14:15], s[28:29], v[2:3] op_sel_hi:[1,0,1]
	global_store_dwordx4 v250, v[0:3], s[66:67] offset:576
	s_cbranch_vccz .LBB0_1029

; DEVI void ph_outproj(const Params& p, int layer, char* shm) {
;     ...
;     auto ep = [&](Acc256& acc) {
;         EPI_IDX;
;       constexpr float osc = 1.0f;
; #pragma unroll
;       for (int ai = 0; ai < 2; ++ai)
; #pragma unroll
;         for (int bj = 0; bj < 2; ++bj)
; #pragma unroll
;           for (int m = 0; m < 4; ++m)
; #pragma unroll
;             for (int n = 0; n < 2; ++n) {
;               size_t off = (size_t)(brow + ai * 128 + wr * 64 + m * 16 + fr) * 1024 + bcol + bj * 128 + wc * 32 + n * 16 + fq * 4;
;               float4 r = *reinterpret_cast<const float4*>(resid + off);
;               float4 o;
;               o.x = DN_ALPHA * r.x + acc[ai][bj][m][n][0] * osc;
;               o.y = DN_ALPHA * r.y + acc[ai][bj][m][n][1] * osc;
;               o.z = DN_ALPHA * r.z + acc[ai][bj][m][n][2] * osc;
;               o.w = DN_ALPHA * r.w + acc[ai][bj][m][n][3] * osc;
;               *reinterpret_cast<float4*>(outp + off) = o;
;             }
;     };
.LBB0_1832:
	v_mov_b32_e32 v128, v214
	v_readlane_b32 s64, v242, 0
	v_and_b32_e32 v129, 15, v128
	v_ashrrev_i32_e32 v130, 2, v128
	v_and_or_b32 v129, v130, s57, v129
	v_lshrrev_b32_e32 v130, 1, v128
	v_lshrrev_b32_e32 v128, 2, v128
	v_and_b32_e32 v131, 12, v128
	v_add_u32_e32 v128, s60, v129
	v_and_b32_e32 v130, 0x60, v130
	v_ashrrev_i32_e32 v129, 31, v128
	v_or3_b32 v132, v130, v131, s59
	v_lshlrev_b64 v[130:131], 12, v[128:129]
	v_readlane_b32 s70, v242, 6
	v_readlane_b32 s71, v242, 7
	v_lshlrev_b32_e32 v192, 2, v132
	s_mov_b64 s[42:43], 0
	v_lshl_add_u64 v[130:131], s[70:71], 0, v[130:131]
	v_lshl_add_u64 v[134:135], v[130:131], 0, v[192:193]
	s_andn2_b64 vcc, exec, s[6:7]
	v_readlane_b32 s65, v242, 1
	v_readlane_b32 s66, v242, 2
	v_readlane_b32 s67, v242, 3
	v_readlane_b32 s68, v242, 4
	v_readlane_b32 s69, v242, 5
	v_lshl_or_b32 v243, v128, 12, v192
	v_add_u32_e32 v244, 16, v128
	v_lshl_or_b32 v244, v244, 12, v192
	v_add_u32_e32 v245, 32, v128
	v_lshl_or_b32 v245, v245, 12, v192
	v_add_u32_e32 v246, 48, v128
	v_lshl_or_b32 v246, v246, 12, v192
	v_add_u32_e32 v247, 128, v128
	v_lshl_or_b32 v247, v247, 12, v192
	v_add_u32_e32 v248, 144, v128
	v_lshl_or_b32 v248, v248, 12, v192
	v_add_u32_e32 v249, 160, v128
	v_lshl_or_b32 v249, v249, 12, v192
	v_add_u32_e32 v250, 176, v128
	v_lshl_or_b32 v250, v250, 12, v192
	global_load_dwordx4 v[130:133], v243, s[70:71]
	global_load_dwordx4 v[134:137], v243, s[70:71] offset:64
	global_load_dwordx4 v[252:255], v244, s[70:71]
	s_waitcnt vmcnt(2)
	v_pk_fma_f32 v[124:125], v[130:131], s[38:39], v[124:125] op_sel_hi:[1,0,1]
	v_pk_fma_f32 v[126:127], v[132:133], s[38:39], v[126:127] op_sel_hi:[1,0,1]
	global_store_dwordx4 v243, v[124:127], s[70:71]
	global_load_dwordx4 v[124:127], v244, s[70:71] offset:64
	s_waitcnt vmcnt(3)
	v_pk_fma_f32 v[120:121], v[134:135], s[38:39], v[120:121] op_sel_hi:[1,0,1]
	v_pk_fma_f32 v[122:123], v[136:137], s[38:39], v[122:123] op_sel_hi:[1,0,1]
	global_store_dwordx4 v243, v[120:123], s[70:71] offset:64
	global_load_dwordx4 v[120:123], v245, s[70:71]
	s_waitcnt vmcnt(4)
	v_pk_fma_f32 v[116:117], v[252:253], s[38:39], v[116:117] op_sel_hi:[1,0,1]
	v_pk_fma_f32 v[118:119], v[254:255], s[38:39], v[118:119] op_sel_hi:[1,0,1]
	global_store_dwordx4 v244, v[116:119], s[70:71]
	global_load_dwordx4 v[116:119], v245, s[70:71] offset:64
	s_waitcnt vmcnt(4)
	v_pk_fma_f32 v[112:113], v[124:125], s[38:39], v[112:113] op_sel_hi:[1,0,1]
	v_pk_fma_f32 v[114:115], v[126:127], s[38:39], v[114:115] op_sel_hi:[1,0,1]
	global_store_dwordx4 v244, v[112:115], s[70:71] offset:64
	global_load_dwordx4 v[112:115], v246, s[70:71]
	s_waitcnt vmcnt(4)
	v_pk_fma_f32 v[108:109], v[120:121], s[38:39], v[108:109] op_sel_hi:[1,0,1]
	v_pk_fma_f32 v[110:111], v[122:123], s[38:39], v[110:111] op_sel_hi:[1,0,1]
	global_store_dwordx4 v245, v[108:111], s[70:71]
	global_load_dwordx4 v[108:111], v246, s[70:71] offset:64
	s_waitcnt vmcnt(4)
	v_pk_fma_f32 v[104:105], v[116:117], s[38:39], v[104:105] op_sel_hi:[1,0,1]
	v_pk_fma_f32 v[106:107], v[118:119], s[38:39], v[106:107] op_sel_hi:[1,0,1]
	global_store_dwordx4 v245, v[104:107], s[70:71] offset:64
	global_load_dwordx4 v[104:107], v243, s[70:71] offset:512
	s_waitcnt vmcnt(4)
	v_pk_fma_f32 v[100:101], v[112:113], s[38:39], v[100:101] op_sel_hi:[1,0,1]
	v_pk_fma_f32 v[102:103], v[114:115], s[38:39], v[102:103] op_sel_hi:[1,0,1]
	global_store_dwordx4 v246, v[100:103], s[70:71]
	global_load_dwordx4 v[100:103], v243, s[70:71] offset:576
	s_waitcnt vmcnt(4)
	v_pk_fma_f32 v[96:97], v[108:109], s[38:39], v[96:97] op_sel_hi:[1,0,1]
	v_pk_fma_f32 v[98:99], v[110:111], s[38:39], v[98:99] op_sel_hi:[1,0,1]
	global_store_dwordx4 v246, v[96:99], s[70:71] offset:64
	global_load_dwordx4 v[96:99], v244, s[70:71] offset:512
	s_waitcnt vmcnt(4)
	v_pk_fma_f32 v[92:93], v[104:105], s[38:39], v[92:93] op_sel_hi:[1,0,1]
	v_pk_fma_f32 v[94:95], v[106:107], s[38:39], v[94:95] op_sel_hi:[1,0,1]
	global_store_dwordx4 v243, v[92:95], s[70:71] offset:512
	global_load_dwordx4 v[92:95], v244, s[70:71] offset:576
	s_waitcnt vmcnt(4)
	v_pk_fma_f32 v[88:89], v[100:101], s[38:39], v[88:89] op_sel_hi:[1,0,1]
	v_pk_fma_f32 v[90:91], v[102:103], s[38:39], v[90:91] op_sel_hi:[1,0,1]
	global_store_dwordx4 v243, v[88:91], s[70:71] offset:576
	global_load_dwordx4 v[88:91], v245, s[70:71] offset:512
	s_waitcnt vmcnt(4)
	v_pk_fma_f32 v[84:85], v[96:97], s[38:39], v[84:85] op_sel_hi:[1,0,1]
	v_pk_fma_f32 v[86:87], v[98:99], s[38:39], v[86:87] op_sel_hi:[1,0,1]
	global_store_dwordx4 v244, v[84:87], s[70:71] offset:512
	global_load_dwordx4 v[84:87], v245, s[70:71] offset:576
	s_waitcnt vmcnt(4)
	v_pk_fma_f32 v[80:81], v[92:93], s[38:39], v[80:81] op_sel_hi:[1,0,1]
	v_pk_fma_f32 v[82:83], v[94:95], s[38:39], v[82:83] op_sel_hi:[1,0,1]
	global_store_dwordx4 v244, v[80:83], s[70:71] offset:576
	global_load_dwordx4 v[80:83], v246, s[70:71] offset:512
	s_waitcnt vmcnt(4)
	v_pk_fma_f32 v[76:77], v[88:89], s[38:39], v[76:77] op_sel_hi:[1,0,1]
	v_pk_fma_f32 v[78:79], v[90:91], s[38:39], v[78:79] op_sel_hi:[1,0,1]
	global_store_dwordx4 v245, v[76:79], s[70:71] offset:512
	global_load_dwordx4 v[76:79], v246, s[70:71] offset:576
	s_waitcnt vmcnt(4)
; DEVI void ph_outproj(const Params& p, int layer, char* shm) {
;     ...
;     auto ep = [&](Acc256& acc) {
;         EPI_IDX;
;       constexpr float osc = 1.0f;
; #pragma unroll
;       for (int ai = 0; ai < 2; ++ai)
; #pragma unroll
;         for (int bj = 0; bj < 2; ++bj)
; #pragma unroll
;           for (int m = 0; m < 4; ++m)
; #pragma unroll
;             for (int n = 0; n < 2; ++n) {
;               size_t off = (size_t)(brow + ai * 128 + wr * 64 + m * 16 + fr) * 1024 + bcol + bj * 128 + wc * 32 + n * 16 + fq * 4;
;               float4 r = *reinterpret_cast<const float4*>(resid + off);
;               float4 o;
;               o.x = DN_ALPHA * r.x + acc[ai][bj][m][n][0] * osc;
;               o.y = DN_ALPHA * r.y + acc[ai][bj][m][n][1] * osc;
;               o.z = DN_ALPHA * r.z + acc[ai][bj][m][n][2] * osc;
;               o.w = DN_ALPHA * r.w + acc[ai][bj][m][n][3] * osc;
;               *reinterpret_cast<float4*>(outp + off) = o;
;             }
;     };
	v_pk_fma_f32 v[72:73], v[84:85], s[38:39], v[72:73] op_sel_hi:[1,0,1]
	v_pk_fma_f32 v[74:75], v[86:87], s[38:39], v[74:75] op_sel_hi:[1,0,1]
	global_store_dwordx4 v245, v[72:75], s[70:71] offset:576
	global_load_dwordx4 v[72:75], v247, s[70:71]
	s_waitcnt vmcnt(4)
	v_pk_fma_f32 v[68:69], v[80:81], s[38:39], v[68:69] op_sel_hi:[1,0,1]
	v_pk_fma_f32 v[70:71], v[82:83], s[38:39], v[70:71] op_sel_hi:[1,0,1]
	global_store_dwordx4 v246, v[68:71], s[70:71] offset:512
	global_load_dwordx4 v[68:71], v247, s[70:71] offset:64
	s_waitcnt vmcnt(4)
	v_pk_fma_f32 v[64:65], v[76:77], s[38:39], v[64:65] op_sel_hi:[1,0,1]
	v_pk_fma_f32 v[66:67], v[78:79], s[38:39], v[66:67] op_sel_hi:[1,0,1]
	global_store_dwordx4 v246, v[64:67], s[70:71] offset:576
	global_load_dwordx4 v[64:67], v248, s[70:71]
	s_waitcnt vmcnt(4)
	v_pk_fma_f32 v[60:61], v[72:73], s[38:39], v[60:61] op_sel_hi:[1,0,1]
	v_pk_fma_f32 v[62:63], v[74:75], s[38:39], v[62:63] op_sel_hi:[1,0,1]
	global_store_dwordx4 v247, v[60:63], s[70:71]
	global_load_dwordx4 v[60:63], v248, s[70:71] offset:64
	s_waitcnt vmcnt(4)
	v_pk_fma_f32 v[56:57], v[68:69], s[38:39], v[56:57] op_sel_hi:[1,0,1]
	v_pk_fma_f32 v[58:59], v[70:71], s[38:39], v[58:59] op_sel_hi:[1,0,1]
	global_store_dwordx4 v247, v[56:59], s[70:71] offset:64
	global_load_dwordx4 v[56:59], v249, s[70:71]
	s_waitcnt vmcnt(4)
	v_pk_fma_f32 v[52:53], v[64:65], s[38:39], v[52:53] op_sel_hi:[1,0,1]
	v_pk_fma_f32 v[54:55], v[66:67], s[38:39], v[54:55] op_sel_hi:[1,0,1]
	global_store_dwordx4 v248, v[52:55], s[70:71]
	global_load_dwordx4 v[52:55], v249, s[70:71] offset:64
	s_waitcnt vmcnt(4)
	v_pk_fma_f32 v[48:49], v[60:61], s[38:39], v[48:49] op_sel_hi:[1,0,1]
	v_pk_fma_f32 v[50:51], v[62:63], s[38:39], v[50:51] op_sel_hi:[1,0,1]
	global_store_dwordx4 v248, v[48:51], s[70:71] offset:64
	global_load_dwordx4 v[48:51], v250, s[70:71]
	s_waitcnt vmcnt(4)
	v_pk_fma_f32 v[44:45], v[56:57], s[38:39], v[44:45] op_sel_hi:[1,0,1]
	v_pk_fma_f32 v[46:47], v[58:59], s[38:39], v[46:47] op_sel_hi:[1,0,1]
	global_store_dwordx4 v249, v[44:47], s[70:71]
	global_load_dwordx4 v[44:47], v250, s[70:71] offset:64
	s_waitcnt vmcnt(4)
	v_pk_fma_f32 v[40:41], v[52:53], s[38:39], v[40:41] op_sel_hi:[1,0,1]
	v_pk_fma_f32 v[42:43], v[54:55], s[38:39], v[42:43] op_sel_hi:[1,0,1]
	global_store_dwordx4 v249, v[40:43], s[70:71] offset:64
	global_load_dwordx4 v[40:43], v247, s[70:71] offset:512
	s_waitcnt vmcnt(4)
	v_pk_fma_f32 v[36:37], v[48:49], s[38:39], v[36:37] op_sel_hi:[1,0,1]
	v_pk_fma_f32 v[38:39], v[50:51], s[38:39], v[38:39] op_sel_hi:[1,0,1]
	global_store_dwordx4 v250, v[36:39], s[70:71]
	global_load_dwordx4 v[36:39], v247, s[70:71] offset:576
	s_waitcnt vmcnt(4)
	v_pk_fma_f32 v[32:33], v[44:45], s[38:39], v[32:33] op_sel_hi:[1,0,1]
	v_pk_fma_f32 v[34:35], v[46:47], s[38:39], v[34:35] op_sel_hi:[1,0,1]
	global_store_dwordx4 v250, v[32:35], s[70:71] offset:64
	global_load_dwordx4 v[32:35], v248, s[70:71] offset:512
	s_waitcnt vmcnt(4)
	v_pk_fma_f32 v[28:29], v[40:41], s[38:39], v[28:29] op_sel_hi:[1,0,1]
	v_pk_fma_f32 v[30:31], v[42:43], s[38:39], v[30:31] op_sel_hi:[1,0,1]
	global_store_dwordx4 v247, v[28:31], s[70:71] offset:512
	global_load_dwordx4 v[28:31], v248, s[70:71] offset:576
	s_waitcnt vmcnt(4)
	v_pk_fma_f32 v[24:25], v[36:37], s[38:39], v[24:25] op_sel_hi:[1,0,1]
	v_pk_fma_f32 v[26:27], v[38:39], s[38:39], v[26:27] op_sel_hi:[1,0,1]
	global_store_dwordx4 v247, v[24:27], s[70:71] offset:576
	global_load_dwordx4 v[24:27], v249, s[70:71] offset:512
	s_waitcnt vmcnt(4)
	v_pk_fma_f32 v[20:21], v[32:33], s[38:39], v[20:21] op_sel_hi:[1,0,1]
	v_pk_fma_f32 v[22:23], v[34:35], s[38:39], v[22:23] op_sel_hi:[1,0,1]
	global_store_dwordx4 v248, v[20:23], s[70:71] offset:512
	global_load_dwordx4 v[20:23], v249, s[70:71] offset:576
	s_waitcnt vmcnt(4)
	v_pk_fma_f32 v[16:17], v[28:29], s[38:39], v[16:17] op_sel_hi:[1,0,1]
	v_pk_fma_f32 v[18:19], v[30:31], s[38:39], v[18:19] op_sel_hi:[1,0,1]
	global_store_dwordx4 v248, v[16:19], s[70:71] offset:576
	global_load_dwordx4 v[16:19], v250, s[70:71] offset:512
	s_waitcnt vmcnt(4)
	v_pk_fma_f32 v[12:13], v[24:25], s[38:39], v[12:13] op_sel_hi:[1,0,1]
	v_pk_fma_f32 v[14:15], v[26:27], s[38:39], v[14:15] op_sel_hi:[1,0,1]
	global_store_dwordx4 v249, v[12:15], s[70:71] offset:512
	global_load_dwordx4 v[12:15], v250, s[70:71] offset:576
	s_waitcnt vmcnt(4)
	v_pk_fma_f32 v[8:9], v[20:21], s[38:39], v[8:9] op_sel_hi:[1,0,1]
	v_pk_fma_f32 v[10:11], v[22:23], s[38:39], v[10:11] op_sel_hi:[1,0,1]
	global_store_dwordx4 v249, v[8:11], s[70:71] offset:576
	s_waitcnt vmcnt(3)
	v_pk_fma_f32 v[4:5], v[16:17], s[38:39], v[4:5] op_sel_hi:[1,0,1]
	v_pk_fma_f32 v[6:7], v[18:19], s[38:39], v[6:7] op_sel_hi:[1,0,1]
	global_store_dwordx4 v250, v[4:7], s[70:71] offset:512
	s_waitcnt vmcnt(2)
	v_pk_fma_f32 v[0:1], v[12:13], s[38:39], v[0:1] op_sel_hi:[1,0,1]
	v_pk_fma_f32 v[2:3], v[14:15], s[38:39], v[2:3] op_sel_hi:[1,0,1]
	global_store_dwordx4 v250, v[0:3], s[70:71] offset:576
	s_cbranch_vccz .LBB0_1865
